# combo: v67 + decode-item DPP + G1 tail prefetch + barrier direct release + LRU read hoist + attention RoPE early loads
# speedup vs baseline: 1.0062x; 1.0042x over previous
; DI unsigned xb_ld(unsigned* p)              { return __hip_atomic_load(p, __ATOMIC_RELAXED, __HIP_MEMORY_SCOPE_AGENT); }
; DI unsigned xb_add(unsigned* p, unsigned v) { return __hip_atomic_fetch_add(p, v, __ATOMIC_RELAXED, __HIP_MEMORY_SCOPE_AGENT); }
; #define XB_SPIN(cond, bar) do { unsigned _sp = 0; while (cond) { __builtin_amdgcn_s_sleep(1); \
;     if ((++_sp & 255u) == 0u) { if (xb_ld(&(bar)[XB_TMO])) break; if (_sp > XB_SPIN_CAP) { atomicAdd(&(bar)[XB_TMO], 1u); break; } } } } while (0)
; DI void xcd_barrier(const XcdBarrier& b) {
;     ...
;   if (threadIdx.x == 0) {
;     unsigned* bar = b.bar;
;     __builtin_amdgcn_s_waitcnt(0);
;     unsigned nloc = b.st[0], nx = b.st[1];
;     if (nloc == 0u) { xcd_barrier_complete(bar, b.x, nloc, nx); b.st[0] = nloc; b.st[1] = nx; }
;     const unsigned old = xb_add(&bar[XB_XSUB(b.x)], 1u);
;     const unsigned gen = old / nloc;
;     if (old + 1u == (gen + 1u) * nloc) {
;       __builtin_amdgcn_fence(__ATOMIC_RELEASE, "agent");
;       asm volatile("s_waitcnt vmcnt(0)" ::: "memory");
;       const unsigned og = xb_add(&bar[XB_TOP], 1u);
;       const unsigned tg = og / nx;
;       if (og + 1u == (tg + 1u) * nx) xb_add(&bar[XB_TOPGEN], 1u);
;       else XB_SPIN(xb_ld(&bar[XB_TOPGEN]) == tg, bar);
;       __builtin_amdgcn_fence(__ATOMIC_ACQUIRE, "agent");
;       xb_add(&bar[XB_XGEN(b.x)], 1u);
;       asm volatile("s_waitcnt vmcnt(0)" ::: "memory");
;     } else {
;       XB_SPIN(xb_ld(&bar[XB_XGEN(b.x)]) == gen, bar);
;       __builtin_amdgcn_fence(__ATOMIC_ACQUIRE, "agent");
;       asm volatile("s_waitcnt vmcnt(0)" ::: "memory");
;     }
.LBB0_236:
	s_or_b64 exec, exec, s[6:7]
	s_and_saveexec_b64 s[6:7], s[8:9]
	s_cbranch_execz .LBB0_238
	v_readlane_b32 s98, v254, 0
	v_readlane_b32 s99, v254, 1
	s_nop 4
	global_atomic_add v161, v183, s[98:99] offset:-4096
	global_atomic_add v161, v183, s[98:99] offset:-3840
	global_atomic_add v161, v183, s[98:99] offset:-3584
	global_atomic_add v161, v183, s[98:99] offset:-3328
	global_atomic_add v161, v183, s[98:99] offset:-3072
	global_atomic_add v161, v183, s[98:99] offset:-2816
	global_atomic_add v161, v183, s[98:99] offset:-2560
	global_atomic_add v161, v183, s[98:99] offset:-2304
	global_atomic_add v161, v183, s[98:99] offset:-2048
	global_atomic_add v161, v183, s[98:99] offset:-1792
	global_atomic_add v161, v183, s[98:99] offset:-1536
	global_atomic_add v161, v183, s[98:99] offset:-1280
	global_atomic_add v161, v183, s[98:99] offset:-1024
	global_atomic_add v161, v183, s[98:99] offset:-768
	global_atomic_add v161, v183, s[98:99] offset:-512
	global_atomic_add v161, v183, s[98:99] offset:-256
	s_nop 0
	s_nop 0
	s_nop 0
	s_nop 0
	s_nop 0
	s_nop 0
	s_nop 0
	s_nop 0
	s_nop 0
	s_nop 0
	s_nop 0
	s_nop 0
	s_nop 0
	s_nop 0
	s_nop 0
	s_nop 0
	s_nop 0
	s_nop 0
	s_nop 0
	s_nop 0
	s_nop 0
	s_nop 0
	s_nop 0
	s_nop 0
	s_nop 0
	s_nop 0
	s_nop 0
	global_atomic_add v[0:1], v183, off
.LBB0_238:
	s_or_b64 exec, exec, s[6:7]
	s_mov_b64 s[6:7], exec
	v_mbcnt_lo_u32_b32 v0, s6, 0
	v_mbcnt_hi_u32_b32 v0, s7, v0
	v_cmp_eq_u32_e32 vcc, 0, v0
	s_waitcnt vmcnt(0)
	buffer_inv sc1
	s_and_saveexec_b64 s[8:9], vcc
	s_cbranch_execz .LBB0_240
	s_bcnt1_i32_b64 s2, s[6:7]
	v_readlane_b32 s6, v253, 62
	v_mov_b32_e32 v0, s2
	v_readlane_b32 s7, v253, 63
	s_nop 4
	s_nop 0
	s_nop 0

; PH void attn_prompt_item(const Params& p, int layer, int item) {
;     ...
; #pragma unroll 1
;   for (int c = 0; c < 4; ++c) {
;     const int q0 = 32 * c;
;     u32x4 cq[2][3];
; #pragma unroll
;     for (int qt = 0; qt < 2; ++qt) { cq[qt][0] = nq[qt][0]; cq[qt][1] = nq[qt][1]; cq[qt][2] = nq[qt][2]; }
;     {
;       const int qn = 32 * ((c < 3) ? (c + 1) : c);
; #pragma unroll
;       for (int qt = 0; qt < 2; ++qt) {
;         const u16* src = PROJ + (size_t)(b * 2048 + nb * 128 + qn + qt * 16 + l15) * NPAD + h * 64;
;         nq[qt][0] = *(const u32x4*)(src + quad * 8);
;         nq[qt][1] = *(const u32x4*)(src + 32 + quad * 8);
;         nq[qt][2] = *(const u32x4*)(src + (quad ^ 1) * 8);
;       }
;     }
;     uint2 gpre[2][4];
; #pragma unroll
;     for (int qt = 0; qt < 2; ++qt)
; #pragma unroll
;       for (int dt = 0; dt < 4; ++dt)
;         gpre[qt][dt] = *(const uint2*)(PROJ + (size_t)(b * 2048 + nb * 128 + q0 + qt * 16 + l15) * NPAD + C_GA + h * 64 + dt * 16 + quad * 4);
;     bf16x8 qf[2][2];
; #pragma unroll
;     for (int qt = 0; qt < 2; ++qt) {
;       const int qi = q0 + qt * 16 + l15;
;       const int tpos = nb * 128 + qi;
;       float own[8], o1[8];
;       unpack8v(cq[qt][0], own);
;       unpack8v(cq[qt][1], o1);
;       if (quad < 2) {
;         float pr[8];
;         unpack8v(cq[qt][2], pr);
;         const float* cs = ROPE + (size_t)tpos * 16;
;         const float sg = (quad == 0) ? -1.f : 1.f;
; #pragma unroll
;         for (int i = 0; i < 8; ++i) own[i] = own[i] * cs[2 * i] + sg * pr[i] * cs[2 * i + 1];
.LBB0_282:
	s_add_i32 s2, s15, 1
	s_lshl_b32 s0, s2, 5
	s_cmp_lg_u32 s15, 3
	s_cselect_b32 s0, s0, 0x60
	v_add_u32_e32 v10, s0, v154
	v_mad_u64_u32 v[8:9], s[0:1], v10, s97, v[116:117]
	v_or_b32_e32 v10, 16, v10
	v_mad_u64_u32 v[16:17], s[0:1], v10, s97, v[116:117]
	s_lshl_b32 s7, s15, 5
	v_add_u32_e32 v44, s7, v154
	s_movk_i32 s0, 0x1380
	v_mul_lo_u32 v44, v44, s0
	v_mov_b32_e32 v45, v161
	v_mov_b32_e32 v133, v161
	v_lshl_add_u64 v[46:47], v[44:45], 1, v[128:129]
	v_add_u32_e32 v44, 0x13800, v44
	s_waitcnt vmcnt(5)
	v_add_u32_e32 v222, s7, v153
	v_lshlrev_b32_e32 v222, 4, v222
	v_mov_b32_e32 v223, v161
	v_lshl_add_u64 v[222:223], v[222:223], 2, s[30:31]
	global_load_dwordx4 v[224:227], v[222:223], off offset:48
	global_load_dwordx4 v[228:231], v[222:223], off offset:32
	global_load_dwordx4 v[232:235], v[222:223], off offset:16
	global_load_dwordx4 v[236:239], v[222:223], off
	global_load_dwordx4 v[240:243], v[222:223], off offset:1072
	global_load_dwordx4 v[244:247], v[222:223], off offset:1056
	global_load_dwordx4 v[248:251], v[222:223], off offset:1040
	global_load_dwordx2 v[156:157], v[222:223], off offset:1024
	global_load_dwordx2 v[222:223], v[222:223], off offset:1032
	v_mov_b64_e32 v[54:55], v[2:3]
	v_lshl_add_u64 v[4:5], v[8:9], 0, v[160:161]
	v_lshl_add_u64 v[8:9], v[8:9], 0, v[132:133]
	v_lshl_add_u64 v[18:19], v[16:17], 0, v[160:161]
	v_lshl_add_u64 v[20:21], v[16:17], 0, v[132:133]
	v_lshl_add_u64 v[44:45], v[44:45], 1, v[128:129]
	v_mov_b64_e32 v[52:53], v[0:1]
	global_load_dwordx4 v[0:3], v[4:5], off
	s_nop 0
	global_load_dwordx4 v[4:7], v[4:5], off offset:64
	s_nop 0
	global_load_dwordx4 v[8:11], v[8:9], off
	s_nop 0
	global_load_dwordx4 v[12:15], v[18:19], off
	s_nop 0
	global_load_dwordx4 v[16:19], v[18:19], off offset:64
	s_nop 0
	global_load_dwordx4 v[20:23], v[20:21], off
	s_nop 0
	global_load_dwordx2 v[148:149], v[46:47], off offset:1536
	global_load_dwordx2 v[146:147], v[46:47], off offset:1568
	global_load_dwordx2 v[144:145], v[46:47], off offset:1600
	global_load_dwordx2 v[142:143], v[46:47], off offset:1632
	global_load_dwordx2 v[140:141], v[44:45], off offset:1536
	global_load_dwordx2 v[138:139], v[44:45], off offset:1568
	global_load_dwordx2 v[136:137], v[44:45], off offset:1600
	global_load_dwordx2 v[134:135], v[44:45], off offset:1632
	v_add_u32_e32 v56, s7, v153
	v_lshlrev_b32_e32 v50, 16, v52
	v_and_b32_e32 v51, 0xffff0000, v52
	v_lshlrev_b32_e32 v48, 16, v53
	v_and_b32_e32 v49, 0xffff0000, v53
	v_lshlrev_b32_e32 v46, 16, v54
	v_and_b32_e32 v47, 0xffff0000, v54
	v_lshlrev_b32_e32 v44, 16, v55
	v_and_b32_e32 v45, 0xffff0000, v55
	v_lshlrev_b32_e32 v52, 4, v56
	s_and_saveexec_b64 s[0:1], s[36:37]
	s_cbranch_execz .LBB0_284
	v_mov_b32_e32 v53, v161
	v_lshl_add_u64 v[54:55], v[52:53], 2, s[30:31]
	s_waitcnt vmcnt(26)
	v_lshlrev_b32_e32 v60, 16, v40
	v_and_b32_e32 v61, 0xffff0000, v40
	v_lshlrev_b32_e32 v74, 16, v41
	v_and_b32_e32 v75, 0xffff0000, v41
	v_lshlrev_b32_e32 v76, 16, v42
	v_and_b32_e32 v77, 0xffff0000, v42
	v_lshlrev_b32_e32 v78, 16, v43
	v_and_b32_e32 v79, 0xffff0000, v43
	s_waitcnt vmcnt(19)
	v_mov_b64_e32 v[40:41], v[224:225]
	v_mov_b64_e32 v[42:43], v[226:227]
	v_mov_b64_e32 v[62:63], v[228:229]
	v_mov_b64_e32 v[64:65], v[230:231]
	v_mov_b64_e32 v[66:67], v[232:233]
	v_mov_b64_e32 v[68:69], v[234:235]
	v_mov_b64_e32 v[70:71], v[236:237]
	v_mov_b64_e32 v[72:73], v[238:239]
	v_cndmask_b32_e64 v53, v61, -v61, s[38:39]
	v_mov_b32_e32 v61, v51
	v_mov_b32_e32 v51, v53
	v_cndmask_b32_e64 v53, v75, -v75, s[38:39]
	v_cndmask_b32_e64 v60, v60, -v60, s[38:39]
	s_nop 0
	v_mul_f32_e32 v40, v40, v44
	s_nop 0
	v_mov_b32_e32 v58, v63
	s_nop 0
	v_mov_b32_e32 v56, v67
	s_nop 0
	v_mov_b32_e32 v54, v71
	v_mov_b32_e32 v71, v73
	v_pk_mul_f32 v[50:51], v[70:71], v[50:51]
	v_mov_b32_e32 v71, v49
	v_mov_b32_e32 v67, v69
	v_mov_b32_e32 v49, v53
	v_cndmask_b32_e64 v53, v77, -v77, s[38:39]
	v_pk_mul_f32 v[48:49], v[66:67], v[48:49]
	v_mov_b32_e32 v67, v47
	v_mov_b32_e32 v63, v65
	v_mov_b32_e32 v47, v53
	v_pk_mul_f32 v[46:47], v[62:63], v[46:47]
	v_cndmask_b32_e64 v63, v79, -v79, s[38:39]
	v_mov_b32_e32 v62, v45
	v_cndmask_b32_e64 v44, v78, -v78, s[38:39]
	v_pk_mul_f32 v[42:43], v[42:43], v[62:63]
	v_mov_b32_e32 v55, v72
	v_mov_b32_e32 v57, v68
	v_mov_b32_e32 v59, v64
	v_cndmask_b32_e64 v70, v74, -v74, s[38:39]
	v_cndmask_b32_e64 v66, v76, -v76, s[38:39]
	v_mul_f32_e32 v44, v44, v41
	v_mov_b32_e32 v41, v42
	v_mov_b32_e32 v45, v43
	v_pk_fma_f32 v[50:51], v[60:61], v[54:55], v[50:51]
	v_pk_fma_f32 v[48:49], v[70:71], v[56:57], v[48:49]
	v_pk_fma_f32 v[46:47], v[66:67], v[58:59], v[46:47]
	v_pk_add_f32 v[44:45], v[40:41], v[44:45]
; PH void attn_prompt_item(const Params& p, int layer, int item) {
;     ...
;       if (quad < 2) {
;         float pr[8];
;         unpack8v(cq[qt][2], pr);
;         const float* cs = ROPE + (size_t)tpos * 16;
;         const float sg = (quad == 0) ? -1.f : 1.f;
; #pragma unroll
;         for (int i = 0; i < 8; ++i) own[i] = own[i] * cs[2 * i] + sg * pr[i] * cs[2 * i + 1];
;       }
; #pragma unroll
;       for (int i = 0; i < 8; ++i) { own[i] *= 0.125f; o1[i] *= 0.125f; }
;       qf[qt][0] = __builtin_bit_cast(bf16x8, pack8(own));
;       qf[qt][1] = __builtin_bit_cast(bf16x8, pack8(o1));
.LBB0_284:
	s_or_b64 exec, exec, s[0:1]
	s_waitcnt vmcnt(16)
	v_lshlrev_b32_e32 v54, 16, v36
	v_and_b32_e32 v55, 0xffff0000, v36
	v_lshlrev_b32_e32 v42, 16, v37
	v_and_b32_e32 v43, 0xffff0000, v37
	v_lshlrev_b32_e32 v40, 16, v38
	v_and_b32_e32 v41, 0xffff0000, v38
	v_lshlrev_b32_e32 v36, 16, v39
	v_and_b32_e32 v37, 0xffff0000, v39
	s_and_saveexec_b64 s[0:1], s[36:37]
	s_cbranch_execz .LBB0_281
	v_ashrrev_i32_e32 v53, 31, v52
	v_lshl_add_u64 v[38:39], v[52:53], 2, s[30:31]
	s_waitcnt vmcnt(14)
	v_lshlrev_b32_e32 v58, 16, v32
	v_and_b32_e32 v59, 0xffff0000, v32
	v_lshlrev_b32_e32 v72, 16, v33
	v_and_b32_e32 v73, 0xffff0000, v33
	v_lshlrev_b32_e32 v74, 16, v34
	v_and_b32_e32 v75, 0xffff0000, v34
	v_lshlrev_b32_e32 v76, 16, v35
	v_and_b32_e32 v77, 0xffff0000, v35
	v_mov_b64_e32 v[32:33], v[240:241]
	v_mov_b64_e32 v[34:35], v[242:243]
	v_mov_b64_e32 v[60:61], v[244:245]
	v_mov_b64_e32 v[62:63], v[246:247]
	v_mov_b64_e32 v[64:65], v[248:249]
	v_mov_b64_e32 v[66:67], v[250:251]
	v_mov_b64_e32 v[68:69], v[156:157]
	v_mov_b64_e32 v[70:71], v[222:223]
	v_cndmask_b32_e64 v58, v58, -v58, s[38:39]
	s_nop 0
	v_mul_f32_e32 v32, v32, v36
	s_nop 0
	v_mov_b32_e32 v56, v61
	v_cndmask_b32_e64 v61, v59, -v59, s[38:39]
	s_nop 0
	v_mov_b32_e32 v38, v69
	v_mov_b32_e32 v59, v55
	v_mov_b32_e32 v69, v71
	v_mov_b32_e32 v55, v61
	v_cndmask_b32_e64 v61, v73, -v73, s[38:39]
	v_mov_b32_e32 v52, v65
	v_mov_b32_e32 v57, v62
	v_pk_mul_f32 v[54:55], v[68:69], v[54:55]
	v_mov_b32_e32 v69, v43
	v_mov_b32_e32 v65, v67
	v_mov_b32_e32 v43, v61
	v_cndmask_b32_e64 v62, v75, -v75, s[38:39]
	v_pk_mul_f32 v[42:43], v[64:65], v[42:43]
	v_mov_b32_e32 v65, v41
	v_mov_b32_e32 v61, v63
	v_mov_b32_e32 v41, v62
	v_pk_mul_f32 v[40:41], v[60:61], v[40:41]
	v_cndmask_b32_e64 v61, v77, -v77, s[38:39]
	v_mov_b32_e32 v60, v37
	v_cndmask_b32_e64 v36, v76, -v76, s[38:39]
	v_pk_mul_f32 v[34:35], v[34:35], v[60:61]
	v_mov_b32_e32 v39, v70
	v_mov_b32_e32 v53, v66
	v_cndmask_b32_e64 v68, v72, -v72, s[38:39]
	v_cndmask_b32_e64 v64, v74, -v74, s[38:39]
	v_mul_f32_e32 v36, v36, v33
	v_mov_b32_e32 v33, v34
	v_mov_b32_e32 v37, v35
	v_pk_fma_f32 v[54:55], v[58:59], v[38:39], v[54:55]
	v_pk_fma_f32 v[42:43], v[68:69], v[52:53], v[42:43]
	v_pk_fma_f32 v[40:41], v[64:65], v[56:57], v[40:41]
	v_pk_add_f32 v[36:37], v[32:33], v[36:37]
	s_branch .LBB0_281
.LBB0_286:
	s_nop 0
	s_nop 0
	s_nop 0
	s_nop 0
	s_nop 0
	s_nop 0
	s_nop 0
	s_nop 0
	s_nop 0
	s_nop 0
	s_nop 0
	s_nop 0
	s_nop 0
	s_nop 0
	s_nop 0
	s_nop 0
	s_nop 0
	s_nop 0
	s_nop 0
	s_nop 0
	s_nop 0
	s_nop 0
	s_nop 0
	s_nop 0
	s_nop 0
	s_nop 0
	s_nop 0
	s_nop 0
	s_nop 0
	s_nop 0
	s_nop 0
	s_nop 0
	s_mov_b64 s[0:1], 0

; DI float softplus_f(float x) { return x > 20.f ? x : log1pf(__expf(x)); }
; PH void lru_item(const Params& p, int layer, int b, int n, int dpart) {
;     ...
;   const u16* WA = (const u16*)(p.ws + WS_WA) + (size_t)(layer * 8 + n) * 9216;
;   const u16* WX = (const u16*)(p.ws + WS_WX) + (size_t)(layer * 8 + n) * 9216;
;   bf16x8 wa[2][3], wx[2][3];
; #pragma unroll
;   for (int dt = 0; dt < 2; ++dt)
; #pragma unroll
;     for (int ks = 0; ks < 3; ++ks) {
;       const int d = dpart * 32 + dt * 16 + l15, k = ks * 32 + quad * 8;
;       wa[dt][ks] = *(const bf16x8*)(WA + d * 96 + k);
;       wx[dt][ks] = *(const bf16x8*)(WX + d * 96 + k);
;     }
;   const int nchunks = (b >= 0) ? 16 : 1;
;   const int sch = tid & 31, sub = tid >> 5;
;   const int chg = n * 96 + dpart * 32 + sch;
;   const float ba = p.in[14][layer * 768 + chg], bx = p.in[16][layer * 768 + chg];
;   const float cl = -8.f * softplus_f(-p.in[17][layer * 768 + chg]);
.LBB0_403:
	s_and_b64 vcc, exec, s[0:1]
	s_cbranch_vccz .LBB0_619
	s_nop 0
	s_nop 0
	s_nop 0
	s_nop 0
	s_nop 0
	s_nop 0
	s_nop 0
	s_nop 0
	s_nop 0
	s_nop 0
	s_nop 0
	s_nop 0
	s_nop 0
	s_nop 0
	s_nop 0
	s_nop 0
	s_nop 0
	s_nop 0
	s_add_i32 s0, s84, 0xffc0
	s_and_b32 s1, s0, 0xff
	s_mulk_i32 s1, 0xab
	s_bfe_u32 s8, s1, 0x70009
	s_mul_i32 s1, s8, 3
	s_sub_i32 s9, s0, s1
	v_readlane_b32 s0, v255, 46
	s_add_i32 s0, s0, s8
	s_mul_i32 s2, s0, 0x2400
	s_lshl_b64 s[0:1], s[2:3], 1
	v_readlane_b32 s2, v254, 28
	s_add_u32 s6, s2, s0
	v_readlane_b32 s2, v254, 29
	s_addc_u32 s7, s2, s1
	v_readlane_b32 s2, v254, 30
	s_add_u32 s0, s2, s0
	v_readlane_b32 s2, v254, 31
	v_mov_b32_e32 v77, v182
	s_addc_u32 s1, s2, s1
	s_lshl_b32 s2, s9, 5
	s_and_b32 s2, s2, 0xe0
	v_and_b32_e32 v78, 15, v77
	s_waitcnt vmcnt(6)
	v_or_b32_e32 v0, s2, v78
	v_mul_u32_u24_e32 v0, 0x60, v0
	v_bfe_u32 v73, v77, 4, 2
	v_lshlrev_b32_e32 v160, 1, v0
	s_waitcnt lgkmcnt(0)
	v_lshl_add_u64 v[0:1], s[6:7], 0, v[160:161]
	v_lshl_add_u64 v[2:3], s[0:1], 0, v[160:161]
	v_lshlrev_b32_e32 v160, 4, v73
	v_lshl_add_u64 v[0:1], v[0:1], 0, v[160:161]
	v_lshl_add_u64 v[2:3], v[2:3], 0, v[160:161]
	global_load_dwordx4 v[32:35], v[0:1], off
	global_load_dwordx4 v[24:27], v[0:1], off offset:64
	global_load_dwordx4 v[36:39], v[2:3], off
	global_load_dwordx4 v[16:19], v[2:3], off offset:64
	global_load_dwordx4 v[12:15], v[0:1], off offset:128
	global_load_dwordx4 v[40:43], v[0:1], off offset:3072
	global_load_dwordx4 v[8:11], v[2:3], off offset:128
	global_load_dwordx4 v[44:47], v[2:3], off offset:3072
	global_load_dwordx4 v[28:31], v[0:1], off offset:3136
	global_load_dwordx4 v[4:7], v[0:1], off offset:3200
	global_load_dwordx4 v[20:23], v[2:3], off offset:3136
	s_nop 0
	global_load_dwordx4 v[0:3], v[2:3], off offset:3200
	s_mul_i32 s6, s8, 0x60
	v_and_b32_e32 v76, 31, v77
	s_add_i32 s0, s6, s2
	v_or_b32_e32 v116, s0, v76
	v_readlane_b32 s0, v255, 41
	v_readlane_b32 s36, v252, 21
	v_readlane_b32 s37, v252, 22
	v_add_u32_e32 v160, s0, v116
	v_lshlrev_b64 v[50:51], 2, v[160:161]
	v_readlane_b32 s38, v252, 23
	v_readlane_b32 s39, v252, 24
	v_readlane_b32 s40, v252, 25
	v_readlane_b32 s41, v252, 26
	v_readlane_b32 s42, v252, 27
	v_readlane_b32 s43, v252, 28
	v_readlane_b32 s44, v252, 29
	v_readlane_b32 s45, v252, 30
	v_readlane_b32 s46, v252, 31
	v_readlane_b32 s47, v252, 32
	v_readlane_b32 s48, v252, 33
	v_readlane_b32 s49, v252, 34
	v_readlane_b32 s50, v252, 35
	v_readlane_b32 s51, v252, 36
	v_lshl_add_u64 v[48:49], s[48:49], 0, v[50:51]
	v_readlane_b32 s36, v252, 37
	v_readlane_b32 s38, v252, 39
	v_readlane_b32 s39, v252, 40
	global_load_dword v114, v[48:49], off
	v_readlane_b32 s37, v252, 38
	v_lshl_add_u64 v[48:49], s[38:39], 0, v[50:51]
	global_load_dword v48, v[48:49], off
	v_lshl_add_u64 v[50:51], s[36:37], 0, v[50:51]
	global_load_dword v115, v[50:51], off
	s_mov_b32 s0, 0xc1a00000
	v_readlane_b32 s1, v255, 42
	v_readlane_b32 s40, v252, 41
	v_readlane_b32 s41, v252, 42
	v_readlane_b32 s42, v252, 43
	v_readlane_b32 s43, v252, 44
	v_readlane_b32 s44, v252, 45
	v_readlane_b32 s45, v252, 46
	v_readlane_b32 s46, v252, 47
	v_readlane_b32 s47, v252, 48
	v_readlane_b32 s48, v252, 49
	v_readlane_b32 s49, v252, 50
	v_readlane_b32 s50, v252, 51
	v_readlane_b32 s51, v252, 52
	s_waitcnt vmcnt(1)
	v_xor_b32_e32 v117, 0x80000000, v48
	v_cmp_ngt_f32_e32 vcc, s0, v48
	s_and_saveexec_b64 s[0:1], vcc
	s_cbranch_execz .LBB0_406
; DI float softplus_f(float x) { return x > 20.f ? x : log1pf(__expf(x)); }
; PH void lru_item(const Params& p, int layer, int b, int n, int dpart) {
;     ...
;   const float cl = -8.f * softplus_f(-p.in[17][layer * 768 + chg]);
	v_mul_f32_e32 v48, 0xbfb8aa3b, v48
	v_exp_f32_e32 v62, v48
	s_mov_b32 s7, 0x3f2aaaab
	v_add_f32_e32 v50, 1.0, v62
	v_frexp_mant_f32_e32 v52, v50
	v_cvt_f64_f32_e32 v[48:49], v50
	v_frexp_exp_i32_f64_e32 v48, v[48:49]
	v_cmp_gt_f32_e32 vcc, s7, v52
	v_add_f32_e32 v51, -1.0, v50
	v_sub_f32_e32 v53, v51, v50
	v_subbrev_co_u32_e32 v56, vcc, 0, v48, vcc
	v_sub_u32_e32 v48, 0, v56
	v_sub_f32_e32 v51, v62, v51
	v_add_f32_e32 v53, 1.0, v53
	v_ldexp_f32 v49, v50, v48
	v_add_f32_e32 v51, v51, v53
	v_add_f32_e32 v50, -1.0, v49
	v_add_f32_e32 v52, 1.0, v49
	v_ldexp_f32 v48, v51, v48
	v_add_f32_e32 v51, 1.0, v50
	v_add_f32_e32 v53, -1.0, v52
	v_sub_f32_e32 v51, v49, v51
	v_sub_f32_e32 v49, v49, v53
	v_add_f32_e32 v51, v48, v51
	v_add_f32_e32 v48, v48, v49
	v_add_f32_e32 v57, v52, v48
	v_rcp_f32_e32 v59, v57
	v_sub_f32_e32 v49, v57, v52
	v_sub_f32_e32 v58, v48, v49
	v_add_f32_e32 v49, v50, v51
	v_mul_f32_e32 v61, v49, v59
	v_sub_f32_e32 v48, v49, v50
	v_mul_f32_e32 v50, v57, v61
	v_fma_f32 v52, v61, v57, -v50
	v_fmac_f32_e32 v52, v61, v58
	v_sub_f32_e32 v60, v51, v48
	v_add_f32_e32 v48, v50, v52
	v_sub_f32_e32 v51, v49, v48
	v_pk_add_f32 v[54:55], v[48:49], v[50:51] neg_lo:[0,1] neg_hi:[0,1]
	v_mov_b32_e32 v53, v48
	v_pk_add_f32 v[48:49], v[54:55], v[52:53] neg_lo:[0,1] neg_hi:[0,1]
	s_mov_b32 s7, 0x3f317218
	v_add_f32_e32 v49, v60, v49
	v_add_f32_e32 v48, v48, v49
	v_add_f32_e32 v49, v51, v48
	v_mul_f32_e32 v60, v59, v49
	v_mul_f32_e32 v50, v57, v60
	v_fma_f32 v52, v60, v57, -v50
	v_fmac_f32_e32 v52, v60, v58
	v_sub_f32_e32 v51, v51, v49
	v_add_f32_e32 v57, v48, v51
	v_add_f32_e32 v48, v50, v52
	v_sub_f32_e32 v51, v49, v48
	v_pk_add_f32 v[54:55], v[48:49], v[50:51] neg_lo:[0,1] neg_hi:[0,1]
	v_mov_b32_e32 v53, v48
	v_pk_add_f32 v[48:49], v[54:55], v[52:53] neg_lo:[0,1] neg_hi:[0,1]
	s_nop 0
	v_add_f32_e32 v49, v57, v49
	v_add_f32_e32 v48, v48, v49
	v_add_f32_e32 v49, v61, v60
	v_add_f32_e32 v48, v51, v48
	v_sub_f32_e32 v50, v49, v61
	v_mul_f32_e32 v48, v59, v48
	v_sub_f32_e32 v50, v60, v50
	v_add_f32_e32 v50, v50, v48
	v_add_f32_e32 v52, v49, v50
	v_mul_f32_e32 v53, v52, v52
	v_fmamk_f32 v48, v53, 0x3e9b6dac, v184
	v_fmaak_f32 v163, v53, v48, 0x3f2aaada
	v_cvt_f32_i32_e32 v48, v56
	v_sub_f32_e32 v49, v52, v49
	v_sub_f32_e32 v49, v50, v49
	v_ldexp_f32 v54, v49, 1
	v_mul_f32_e32 v49, v52, v53
	v_ldexp_f32 v51, v52, 1
	v_pk_mul_f32 v[52:53], v[48:49], v[162:163]
	s_nop 0
	v_fma_f32 v50, v48, s7, -v52
	v_fmac_f32_e32 v50, 0xb102e308, v48
	v_pk_add_f32 v[48:49], v[52:53], v[50:51]
	s_mov_b32 s7, 0x7f800000
	v_sub_f32_e32 v51, v49, v51
	v_sub_f32_e32 v51, v53, v51
	v_add_f32_e32 v55, v54, v51
	v_mov_b32_e32 v54, v52
	v_pk_add_f32 v[52:53], v[48:49], v[52:53] neg_lo:[0,1] neg_hi:[0,1]
	v_pk_add_f32 v[56:57], v[48:49], v[54:55]
	v_mov_b32_e32 v51, v48
	v_mov_b32_e32 v53, v57
	v_pk_add_f32 v[58:59], v[50:51], v[52:53] neg_lo:[0,1] neg_hi:[0,1]
	v_pk_add_f32 v[50:51], v[50:51], v[52:53]
	v_mov_b32_e32 v54, v55
	v_pk_add_f32 v[52:53], v[50:51], v[48:49] op_sel:[1,0] op_sel_hi:[0,1] neg_lo:[0,1] neg_hi:[0,1]
	v_pk_add_f32 v[60:61], v[56:57], v[52:53] op_sel_hi:[1,0] neg_lo:[0,1] neg_hi:[0,1]
	v_mov_b32_e32 v56, v57
	v_mov_b32_e32 v57, v51
	v_pk_mov_b32 v[52:53], v[48:49], v[52:53] op_sel:[1,0]
	v_mov_b32_e32 v55, v48
	v_pk_add_f32 v[52:53], v[56:57], v[52:53] neg_lo:[0,1] neg_hi:[0,1]
	v_mov_b32_e32 v60, v58
	v_pk_add_f32 v[48:49], v[54:55], v[52:53] neg_lo:[0,1] neg_hi:[0,1]
	v_mov_b32_e32 v59, v51
	v_pk_add_f32 v[52:53], v[60:61], v[48:49]
	v_cmp_neq_f32_e32 vcc, s7, v62
	v_pk_add_f32 v[54:55], v[52:53], v[52:53] op_sel:[0,1] op_sel_hi:[1,0]
	s_mov_b32 s7, 0x33800000
	v_pk_add_f32 v[50:51], v[50:51], v[54:55] op_sel:[1,0] op_sel_hi:[0,1]
	v_mov_b32_e32 v53, v50
	v_pk_add_f32 v[56:57], v[52:53], v[58:59] neg_lo:[0,1] neg_hi:[0,1]
	v_mov_b32_e32 v49, v54
	v_sub_f32_e32 v51, v52, v56
	v_pk_add_f32 v[48:49], v[48:49], v[56:57] neg_lo:[0,1] neg_hi:[0,1]
	v_sub_f32_e32 v51, v58, v51
	v_add_f32_e32 v48, v48, v51
	v_add_f32_e32 v48, v48, v49
	v_add_f32_e32 v48, v50, v48
	v_cndmask_b32_e32 v48, v196, v48, vcc
	v_cmp_ngt_f32_e32 vcc, -1.0, v62
	s_nop 1
	v_cndmask_b32_e32 v48, v197, v48, vcc
	v_cmp_neq_f32_e32 vcc, -1.0, v62
	s_nop 1
	v_cndmask_b32_e32 v48, v191, v48, vcc
	v_cmp_lt_f32_e64 vcc, |v62|, s7
	s_nop 1
	v_cndmask_b32_e32 v117, v48, v62, vcc

; __global__ void __launch_bounds__(256, 2) mega(Params p) {
;     ...
;     for (int rep = 0; rep < REP_2B; ++rep) {
;       bool first = true;
;       for (;;) {
;         int it;
;         if (first) { it = (int)blockIdx.x; first = false; }
;         else it = next_item(ctr + layer * 2 + 1 + 8 * rep, &slot) + (int)gridDim.x;
;         if (rep > 0) { it += PROBE_2B_LO; if (it >= PROBE_2B_HI) break; }
;         if (it >= 288 + 192 + 24 + 256 + 1536) break;
;         it = (it < 192) ? (it + 384) : ((it < 480) ? (it - 192) : ((it < 504) ? (it + 608) : ((it < 760) ? (it + 328) : (it + 352))));
;         if (it < 384) { const int v = it % 96; ssd_prompt_item<0>(p, layer, v / 12, v % 12, it / 96); }
;         else if (it < 576) { const int v = it - 384; lru_item(p, layer, v / 24, (v % 24) / 3, v % 3); }
;         else if (it < 832) attn_prompt_item(p, layer, it - 576);
;         else if (it < 1088) attn_decode_item(p, layer, it - 832);
;         else if (it < 1112) { const int v = it - 1088; lru_item(p, layer, -1, v / 3, v % 3); }
;         else { const int v = it - 1112; ssd_decode_item(p, layer, v / 12, v % 12); }
;       }
;       xcd_barrier(xb);
.LBB0_476:
	s_nop 0
	s_nop 0
	s_nop 0
	s_nop 0
	s_nop 0
	s_nop 0
	s_nop 0
	s_nop 0
	s_nop 0
	s_nop 0
	s_nop 0
	s_nop 0
	s_nop 0
	s_nop 0
	s_nop 0
	s_nop 0
	s_nop 0
	s_nop 0
	s_nop 0
	s_nop 0
	s_nop 0
	s_nop 0
	s_nop 0
	s_nop 0
	s_nop 0
	s_nop 0
	s_nop 0
	s_nop 0
	s_nop 0
	s_nop 0
	s_nop 0
	s_nop 0
	s_nop 0
	s_nop 0
	s_nop 0
	s_nop 0
	s_nop 0
	s_nop 0
	s_nop 0
	s_nop 0
	s_nop 0
	s_nop 0
	s_nop 0
	s_nop 0
	s_nop 0
	s_nop 0
	s_cbranch_execnz .LBB0_609

; template <int MODE>
; PH void gemm_phase(const Params& p, int layer) {
;     ...
; #pragma unroll 1
;       for (int j = 0; j < 4; ++j) {
;         const int k0 = ((kq * 4 + j + 20) & 31) * 64;
;         u32x4 rx[4], rw[4];
; #pragma unroll
;         for (int i = 0; i < 4; ++i) {
;           rx[i] = *(const u32x4*)(gX + (size_t)i * 32 * K + k0);
;           rw[i] = *(const u32x4*)(gW + (size_t)i * 32 * K + k0);
;         }
;         __syncthreads();
; #pragma unroll
;         for (int i = 0; i < 4; ++i) {
;           *(u32x4*)(sX + soff + i * 32 * 72) = rx[i];
;           *(u32x4*)(sW + soff + i * 32 * 72) = rw[i];
;         }
.LBB0_770:
	v_readlane_b32 s0, v254, 38
	v_readlane_b32 s1, v254, 39
	s_andn2_b64 vcc, exec, s[0:1]
	s_barrier
	s_cbranch_vccnz .LBB0_846
	s_waitcnt vmcnt(6)
	v_ashrrev_i32_e32 v0, 3, v168
	v_lshlrev_b32_e32 v1, 3, v168
	v_and_b32_e32 v2, 56, v1
	v_ashrrev_i32_e32 v1, 31, v0
	v_readlane_b32 s0, v254, 40
	s_waitcnt vmcnt(4)
	v_lshlrev_b64 v[4:5], 12, v[0:1]
	v_lshl_add_u64 v[4:5], s[28:29], 0, v[4:5]
	v_add_u32_e32 v6, s0, v0
	s_movk_i32 s0, 0x48
	v_ashrrev_i32_e32 v7, 31, v6
	v_mad_u64_u32 v[0:1], s[0:1], v0, s0, v[2:3]
	v_lshlrev_b32_e32 v160, 1, v2
	v_lshlrev_b32_e32 v68, 6, v171
	v_lshlrev_b64 v[6:7], 12, v[6:7]
	v_lshl_add_u64 v[2:3], v[4:5], 0, v[160:161]
	s_mov_b64 s[0:1], 0x4000000
	v_lshl_add_u32 v69, v0, 1, 32
	v_or_b32_e32 v0, v68, v169
	v_and_b32_e32 v1, 48, v168
	v_lshl_or_b32 v74, v170, 6, v169
	v_lshl_add_u64 v[6:7], s[40:41], 0, v[6:7]
	v_lshl_add_u64 v[64:65], v[2:3], 0, s[0:1]
	v_add_u32_e32 v1, 32, v1
	v_mul_lo_u32 v2, v0, s11
	v_mul_u32_u24_e32 v3, 0x90, v74
	v_mov_b32_e32 v0, 0
	v_lshl_add_u64 v[66:67], v[6:7], 0, v[160:161]
	s_mov_b32 s0, 0
	v_add_u32_e32 v70, v1, v2
	v_add_u32_e32 v71, v1, v3
	v_mov_b32_e32 v1, v0
	v_mov_b32_e32 v2, v0
	v_mov_b32_e32 v3, v0
	s_waitcnt vmcnt(1)
	v_mov_b32_e32 v16, v0
	v_mov_b32_e32 v17, v0
	v_mov_b32_e32 v18, v0
	v_mov_b32_e32 v19, v0
	v_mov_b32_e32 v32, v0
	v_mov_b32_e32 v33, v0
	v_mov_b32_e32 v34, v0
	v_mov_b32_e32 v35, v0
	v_mov_b32_e32 v48, v0
	v_mov_b32_e32 v49, v0
	v_mov_b32_e32 v50, v0
	v_mov_b32_e32 v51, v0
	v_mov_b32_e32 v4, v0
	v_mov_b32_e32 v5, v0
	v_mov_b32_e32 v6, v0
	v_mov_b32_e32 v7, v0
	v_mov_b32_e32 v20, v0
	v_mov_b32_e32 v21, v0
	v_mov_b32_e32 v22, v0
	v_mov_b32_e32 v23, v0
	s_waitcnt vmcnt(0)
	v_mov_b32_e32 v36, v0
	v_mov_b32_e32 v37, v0
	v_mov_b32_e32 v38, v0
	v_mov_b32_e32 v39, v0
	v_mov_b32_e32 v52, v0
	v_mov_b32_e32 v53, v0
	v_mov_b32_e32 v54, v0
	v_mov_b32_e32 v55, v0
	v_mov_b32_e32 v8, v0
	v_mov_b32_e32 v9, v0
	v_mov_b32_e32 v10, v0
	v_mov_b32_e32 v11, v0
	v_mov_b32_e32 v24, v0
	v_mov_b32_e32 v25, v0
	v_mov_b32_e32 v26, v0
	v_mov_b32_e32 v27, v0
	v_mov_b32_e32 v40, v0
	v_mov_b32_e32 v41, v0
	v_mov_b32_e32 v42, v0
	v_mov_b32_e32 v43, v0
	v_mov_b32_e32 v56, v0
	v_mov_b32_e32 v57, v0
	v_mov_b32_e32 v58, v0
	v_mov_b32_e32 v59, v0
	v_mov_b32_e32 v12, v0
	v_mov_b32_e32 v13, v0
	v_mov_b32_e32 v14, v0
	v_mov_b32_e32 v15, v0
	v_mov_b32_e32 v28, v0
	v_mov_b32_e32 v29, v0
	v_mov_b32_e32 v30, v0
	v_mov_b32_e32 v31, v0
	v_mov_b32_e32 v44, v0
	v_mov_b32_e32 v45, v0
	v_mov_b32_e32 v46, v0
	v_mov_b32_e32 v47, v0
	v_mov_b32_e32 v60, v0
	v_mov_b32_e32 v61, v0
	v_mov_b32_e32 v62, v0
	v_mov_b32_e32 v63, v0
	s_mov_b32 s99, 0
	v_add_u32_e32 v75, 0x4800, v69
	s_add_i32 s1, s65, 0x0
	s_and_b32 s1, s1, 0x7c0
	s_lshl_b32 s2, s1, 1
	v_lshl_add_u64 v[72:73], v[64:65], 0, s[2:3]
	global_load_dwordx4 v[108:111], v[72:73], off
	v_lshl_add_u64 v[72:73], v[66:67], 0, s[2:3]
	global_load_dwordx4 v[112:115], v[72:73], off
	s_add_u32 s98, s2, s66
	v_lshl_add_u64 v[72:73], v[64:65], 0, s[98:99]
	global_load_dwordx4 v[116:119], v[72:73], off
	v_lshl_add_u64 v[72:73], v[66:67], 0, s[98:99]
	global_load_dwordx4 v[120:123], v[72:73], off
	s_add_u32 s98, s2, s67
	v_lshl_add_u64 v[72:73], v[64:65], 0, s[98:99]
	global_load_dwordx4 v[124:127], v[72:73], off
	v_lshl_add_u64 v[72:73], v[66:67], 0, s[98:99]
	global_load_dwordx4 v[128:131], v[72:73], off
	s_add_u32 s98, s2, s68
	v_lshl_add_u64 v[72:73], v[64:65], 0, s[98:99]
	global_load_dwordx4 v[132:135], v[72:73], off
	v_lshl_add_u64 v[72:73], v[66:67], 0, s[98:99]
	global_load_dwordx4 v[136:139], v[72:73], off
	s_add_i32 s1, s65, 0x40
	s_and_b32 s1, s1, 0x7c0
	s_lshl_b32 s2, s1, 1
	v_lshl_add_u64 v[72:73], v[64:65], 0, s[2:3]
	global_load_dwordx4 v[140:143], v[72:73], off
	v_lshl_add_u64 v[72:73], v[66:67], 0, s[2:3]
	global_load_dwordx4 v[144:147], v[72:73], off
	s_add_u32 s98, s2, s66
	v_lshl_add_u64 v[72:73], v[64:65], 0, s[98:99]
	global_load_dwordx4 v[148:151], v[72:73], off
	v_lshl_add_u64 v[72:73], v[66:67], 0, s[98:99]
	global_load_dwordx4 v[152:155], v[72:73], off
	s_add_u32 s98, s2, s67
	v_lshl_add_u64 v[72:73], v[64:65], 0, s[98:99]
	global_load_dwordx4 v[156:159], v[72:73], off
	v_lshl_add_u64 v[72:73], v[66:67], 0, s[98:99]
	global_load_dwordx4 v[204:207], v[72:73], off
	s_add_u32 s98, s2, s68
	v_lshl_add_u64 v[72:73], v[64:65], 0, s[98:99]
	global_load_dwordx4 v[240:243], v[72:73], off
	v_lshl_add_u64 v[72:73], v[66:67], 0, s[98:99]
	global_load_dwordx4 v[244:247], v[72:73], off
	s_add_i32 s1, s65, 0x80
	s_and_b32 s1, s1, 0x7c0
	s_lshl_b32 s2, s1, 1
	v_lshl_add_u64 v[72:73], v[64:65], 0, s[2:3]
	global_load_dwordx4 v[208:211], v[72:73], off
	v_lshl_add_u64 v[72:73], v[66:67], 0, s[2:3]
	global_load_dwordx4 v[212:215], v[72:73], off
	s_add_u32 s98, s2, s66
	v_lshl_add_u64 v[72:73], v[64:65], 0, s[98:99]
	global_load_dwordx4 v[216:219], v[72:73], off
	v_lshl_add_u64 v[72:73], v[66:67], 0, s[98:99]
	global_load_dwordx4 v[220:223], v[72:73], off
	s_add_u32 s98, s2, s67
	v_lshl_add_u64 v[72:73], v[64:65], 0, s[98:99]
	global_load_dwordx4 v[224:227], v[72:73], off
	v_lshl_add_u64 v[72:73], v[66:67], 0, s[98:99]
	global_load_dwordx4 v[228:231], v[72:73], off
	s_add_u32 s98, s2, s68
	v_lshl_add_u64 v[72:73], v[64:65], 0, s[98:99]
	global_load_dwordx4 v[232:235], v[72:73], off
	v_lshl_add_u64 v[72:73], v[66:67], 0, s[98:99]
	global_load_dwordx4 v[248:251], v[72:73], off
	s_waitcnt vmcnt(23)
	ds_write_b128 v69, v[108:111]
	s_waitcnt vmcnt(22)
	ds_write_b128 v69, v[112:115] offset:36864
	s_waitcnt vmcnt(21)
	ds_write_b128 v69, v[116:119] offset:4608
	s_waitcnt vmcnt(20)
	ds_write_b128 v69, v[120:123] offset:41472
	s_waitcnt vmcnt(19)
	ds_write_b128 v69, v[124:127] offset:9216
	s_waitcnt vmcnt(18)
	ds_write_b128 v69, v[128:131] offset:46080
	s_waitcnt vmcnt(17)
	ds_write_b128 v69, v[132:135] offset:13824
	s_waitcnt vmcnt(16)
	ds_write_b128 v69, v[136:139] offset:50688
	s_waitcnt lgkmcnt(0)
	s_add_i32 s1, s65, 0xc0
	s_and_b32 s1, s1, 0x7c0
	s_lshl_b32 s2, s1, 1
	v_lshl_add_u64 v[72:73], v[64:65], 0, s[2:3]
	global_load_dwordx4 v[108:111], v[72:73], off
	v_lshl_add_u64 v[72:73], v[66:67], 0, s[2:3]
	global_load_dwordx4 v[112:115], v[72:73], off
	s_add_u32 s98, s2, s66
	v_lshl_add_u64 v[72:73], v[64:65], 0, s[98:99]
	global_load_dwordx4 v[116:119], v[72:73], off
	v_lshl_add_u64 v[72:73], v[66:67], 0, s[98:99]
	global_load_dwordx4 v[120:123], v[72:73], off
	s_add_u32 s98, s2, s67
	v_lshl_add_u64 v[72:73], v[64:65], 0, s[98:99]
	global_load_dwordx4 v[124:127], v[72:73], off
	v_lshl_add_u64 v[72:73], v[66:67], 0, s[98:99]
	global_load_dwordx4 v[128:131], v[72:73], off
	s_add_u32 s98, s2, s68
	v_lshl_add_u64 v[72:73], v[64:65], 0, s[98:99]
	global_load_dwordx4 v[132:135], v[72:73], off
	v_lshl_add_u64 v[72:73], v[66:67], 0, s[98:99]
	global_load_dwordx4 v[136:139], v[72:73], off
	s_barrier
; DI f32x4 mfma16(bf16x8 a, bf16x8 b, f32x4 c) { return __builtin_amdgcn_mfma_f32_16x16x32_bf16(a, b, c, 0, 0, 0); }
; template <int MODE>
; PH void gemm_phase(const Params& p, int layer) {
;     ...
; #pragma unroll 1
;       for (int j = 0; j < 4; ++j) {
;         const int k0 = ((kq * 4 + j + 20) & 31) * 64;
;         u32x4 rx[4], rw[4];
; #pragma unroll
;         for (int i = 0; i < 4; ++i) {
;           rx[i] = *(const u32x4*)(gX + (size_t)i * 32 * K + k0);
;           rw[i] = *(const u32x4*)(gW + (size_t)i * 32 * K + k0);
;         }
;         __syncthreads();
; #pragma unroll
;         for (int i = 0; i < 4; ++i) {
;           *(u32x4*)(sX + soff + i * 32 * 72) = rx[i];
;           *(u32x4*)(sW + soff + i * 32 * 72) = rw[i];
;         }
;         __syncthreads();
; #pragma unroll
;         for (int ks = 0; ks < 2; ++ks) {
;           bf16x8 wf[4], xf[4];
; #pragma unroll
;           for (int i = 0; i < 4; ++i) {
;             wf[i] = ldfrag(sW, 72, wn * 64 + i * 16, ks * 32, lane);
;             xf[i] = ldfrag(sX, 72, wm * 64 + i * 16, ks * 32, lane);
;           }
; #pragma unroll
;           for (int nt = 0; nt < 4; ++nt)
; #pragma unroll
;             for (int mt = 0; mt < 4; ++mt) acc[nt][mt] = mfma16(wf[nt], xf[mt], acc[nt][mt]);
;         }
	ds_read_b128 v[76:79], v70 offset:36864
	ds_read_b128 v[80:83], v71
	ds_read_b128 v[84:87], v70 offset:39168
	ds_read_b128 v[88:91], v71 offset:2304
	ds_read_b128 v[92:95], v70 offset:41472
	ds_read_b128 v[96:99], v71 offset:4608
	ds_read_b128 v[100:103], v70 offset:43776
	ds_read_b128 v[104:107], v71 offset:6912
	s_waitcnt lgkmcnt(6)
	v_mfma_f32_16x16x32_bf16 v[60:63], v[76:79], v[80:83], v[60:63]
	s_waitcnt lgkmcnt(4)
	v_mfma_f32_16x16x32_bf16 v[44:47], v[76:79], v[88:91], v[44:47]
	s_waitcnt lgkmcnt(2)
	v_mfma_f32_16x16x32_bf16 v[28:31], v[76:79], v[96:99], v[28:31]
	s_waitcnt lgkmcnt(0)
	v_mfma_f32_16x16x32_bf16 v[12:15], v[76:79], v[104:107], v[12:15]
	v_mfma_f32_16x16x32_bf16 v[56:59], v[84:87], v[80:83], v[56:59]
	v_mfma_f32_16x16x32_bf16 v[40:43], v[84:87], v[88:91], v[40:43]
	v_mfma_f32_16x16x32_bf16 v[24:27], v[84:87], v[96:99], v[24:27]
	v_mfma_f32_16x16x32_bf16 v[8:11], v[84:87], v[104:107], v[8:11]
	v_mfma_f32_16x16x32_bf16 v[52:55], v[92:95], v[80:83], v[52:55]
	v_mfma_f32_16x16x32_bf16 v[36:39], v[92:95], v[88:91], v[36:39]
	v_mfma_f32_16x16x32_bf16 v[20:23], v[92:95], v[96:99], v[20:23]
	v_mfma_f32_16x16x32_bf16 v[4:7], v[92:95], v[104:107], v[4:7]
	v_mfma_f32_16x16x32_bf16 v[48:51], v[100:103], v[80:83], v[48:51]
	v_mfma_f32_16x16x32_bf16 v[32:35], v[100:103], v[88:91], v[32:35]
	v_mfma_f32_16x16x32_bf16 v[16:19], v[100:103], v[96:99], v[16:19]
	v_mfma_f32_16x16x32_bf16 v[0:3], v[100:103], v[104:107], v[0:3]
	ds_read_b128 v[76:79], v70 offset:36928
	ds_read_b128 v[80:83], v71 offset:64
	ds_read_b128 v[84:87], v70 offset:39232
	ds_read_b128 v[88:91], v71 offset:2368
	ds_read_b128 v[92:95], v70 offset:41536
	ds_read_b128 v[96:99], v71 offset:4672
	ds_read_b128 v[100:103], v70 offset:43840
	ds_read_b128 v[104:107], v71 offset:6976
	s_waitcnt lgkmcnt(6)
	v_mfma_f32_16x16x32_bf16 v[60:63], v[76:79], v[80:83], v[60:63]
	s_waitcnt lgkmcnt(4)
	v_mfma_f32_16x16x32_bf16 v[44:47], v[76:79], v[88:91], v[44:47]
	s_waitcnt lgkmcnt(2)
	v_mfma_f32_16x16x32_bf16 v[28:31], v[76:79], v[96:99], v[28:31]
	s_waitcnt lgkmcnt(0)
	v_mfma_f32_16x16x32_bf16 v[12:15], v[76:79], v[104:107], v[12:15]
	v_mfma_f32_16x16x32_bf16 v[56:59], v[84:87], v[80:83], v[56:59]
	v_mfma_f32_16x16x32_bf16 v[40:43], v[84:87], v[88:91], v[40:43]
	v_mfma_f32_16x16x32_bf16 v[24:27], v[84:87], v[96:99], v[24:27]
	v_mfma_f32_16x16x32_bf16 v[8:11], v[84:87], v[104:107], v[8:11]
	v_mfma_f32_16x16x32_bf16 v[52:55], v[92:95], v[80:83], v[52:55]
	v_mfma_f32_16x16x32_bf16 v[36:39], v[92:95], v[88:91], v[36:39]
	v_mfma_f32_16x16x32_bf16 v[20:23], v[92:95], v[96:99], v[20:23]
	v_mfma_f32_16x16x32_bf16 v[4:7], v[92:95], v[104:107], v[4:7]
	v_mfma_f32_16x16x32_bf16 v[48:51], v[100:103], v[80:83], v[48:51]
	v_mfma_f32_16x16x32_bf16 v[32:35], v[100:103], v[88:91], v[32:35]
	v_mfma_f32_16x16x32_bf16 v[16:19], v[100:103], v[96:99], v[16:19]
	v_mfma_f32_16x16x32_bf16 v[0:3], v[100:103], v[104:107], v[0:3]
	s_waitcnt vmcnt(23)
	ds_write_b128 v75, v[140:143]
	s_waitcnt vmcnt(22)
	ds_write_b128 v75, v[144:147] offset:36864
	s_waitcnt vmcnt(21)
	ds_write_b128 v75, v[148:151] offset:4608
	s_waitcnt vmcnt(20)
	ds_write_b128 v75, v[152:155] offset:41472
	s_waitcnt vmcnt(19)
	ds_write_b128 v75, v[156:159] offset:9216
	s_waitcnt vmcnt(18)
	ds_write_b128 v75, v[204:207] offset:46080
	s_waitcnt vmcnt(17)
	ds_write_b128 v75, v[240:243] offset:13824
	s_waitcnt vmcnt(16)
	ds_write_b128 v75, v[244:247] offset:50688
	s_waitcnt lgkmcnt(0)
	s_barrier
	ds_read_b128 v[76:79], v70 offset:55296
	ds_read_b128 v[80:83], v71 offset:18432
	ds_read_b128 v[84:87], v70 offset:57600
	ds_read_b128 v[88:91], v71 offset:20736
	ds_read_b128 v[92:95], v70 offset:59904
	ds_read_b128 v[96:99], v71 offset:23040
	ds_read_b128 v[100:103], v70 offset:62208
	ds_read_b128 v[104:107], v71 offset:25344
	s_waitcnt lgkmcnt(6)
	v_mfma_f32_16x16x32_bf16 v[60:63], v[76:79], v[80:83], v[60:63]
	s_waitcnt lgkmcnt(4)
	v_mfma_f32_16x16x32_bf16 v[44:47], v[76:79], v[88:91], v[44:47]
	s_waitcnt lgkmcnt(2)
	v_mfma_f32_16x16x32_bf16 v[28:31], v[76:79], v[96:99], v[28:31]
	s_waitcnt lgkmcnt(0)
	v_mfma_f32_16x16x32_bf16 v[12:15], v[76:79], v[104:107], v[12:15]
	v_mfma_f32_16x16x32_bf16 v[56:59], v[84:87], v[80:83], v[56:59]
	v_mfma_f32_16x16x32_bf16 v[40:43], v[84:87], v[88:91], v[40:43]
	v_mfma_f32_16x16x32_bf16 v[24:27], v[84:87], v[96:99], v[24:27]
	v_mfma_f32_16x16x32_bf16 v[8:11], v[84:87], v[104:107], v[8:11]
	v_mfma_f32_16x16x32_bf16 v[52:55], v[92:95], v[80:83], v[52:55]
	v_mfma_f32_16x16x32_bf16 v[36:39], v[92:95], v[88:91], v[36:39]
	v_mfma_f32_16x16x32_bf16 v[20:23], v[92:95], v[96:99], v[20:23]
	v_mfma_f32_16x16x32_bf16 v[4:7], v[92:95], v[104:107], v[4:7]
	v_mfma_f32_16x16x32_bf16 v[48:51], v[100:103], v[80:83], v[48:51]
	v_mfma_f32_16x16x32_bf16 v[32:35], v[100:103], v[88:91], v[32:35]
	v_mfma_f32_16x16x32_bf16 v[16:19], v[100:103], v[96:99], v[16:19]
	v_mfma_f32_16x16x32_bf16 v[0:3], v[100:103], v[104:107], v[0:3]
	ds_read_b128 v[76:79], v70 offset:55360
	ds_read_b128 v[80:83], v71 offset:18496
	ds_read_b128 v[84:87], v70 offset:57664
	ds_read_b128 v[88:91], v71 offset:20800
	ds_read_b128 v[92:95], v70 offset:59968
	ds_read_b128 v[96:99], v71 offset:23104
	ds_read_b128 v[100:103], v70 offset:62272
	ds_read_b128 v[104:107], v71 offset:25408
	s_waitcnt lgkmcnt(6)
	v_mfma_f32_16x16x32_bf16 v[60:63], v[76:79], v[80:83], v[60:63]
	s_waitcnt lgkmcnt(4)
	v_mfma_f32_16x16x32_bf16 v[44:47], v[76:79], v[88:91], v[44:47]
	s_waitcnt lgkmcnt(2)
	v_mfma_f32_16x16x32_bf16 v[28:31], v[76:79], v[96:99], v[28:31]
	s_waitcnt lgkmcnt(0)
	v_mfma_f32_16x16x32_bf16 v[12:15], v[76:79], v[104:107], v[12:15]
	v_mfma_f32_16x16x32_bf16 v[56:59], v[84:87], v[80:83], v[56:59]
	v_mfma_f32_16x16x32_bf16 v[40:43], v[84:87], v[88:91], v[40:43]
	v_mfma_f32_16x16x32_bf16 v[24:27], v[84:87], v[96:99], v[24:27]
	v_mfma_f32_16x16x32_bf16 v[8:11], v[84:87], v[104:107], v[8:11]
	v_mfma_f32_16x16x32_bf16 v[52:55], v[92:95], v[80:83], v[52:55]
	v_mfma_f32_16x16x32_bf16 v[36:39], v[92:95], v[88:91], v[36:39]
	v_mfma_f32_16x16x32_bf16 v[20:23], v[92:95], v[96:99], v[20:23]
	v_mfma_f32_16x16x32_bf16 v[4:7], v[92:95], v[104:107], v[4:7]
	v_mfma_f32_16x16x32_bf16 v[48:51], v[100:103], v[80:83], v[48:51]
	v_mfma_f32_16x16x32_bf16 v[32:35], v[100:103], v[88:91], v[32:35]
	v_mfma_f32_16x16x32_bf16 v[16:19], v[100:103], v[96:99], v[16:19]
	v_mfma_f32_16x16x32_bf16 v[0:3], v[100:103], v[104:107], v[0:3]
	s_waitcnt vmcnt(15)
	ds_write_b128 v69, v[208:211]
	s_waitcnt vmcnt(14)
	ds_write_b128 v69, v[212:215] offset:36864
	s_waitcnt vmcnt(13)
	ds_write_b128 v69, v[216:219] offset:4608
	s_waitcnt vmcnt(12)
	ds_write_b128 v69, v[220:223] offset:41472
	s_waitcnt vmcnt(11)
	ds_write_b128 v69, v[224:227] offset:9216
	s_waitcnt vmcnt(10)
	ds_write_b128 v69, v[228:231] offset:46080
	s_waitcnt vmcnt(9)
	ds_write_b128 v69, v[232:235] offset:13824
	s_waitcnt vmcnt(8)
	ds_write_b128 v69, v[248:251] offset:50688
	s_waitcnt lgkmcnt(0)
	s_barrier
; DI f32x4 mfma16(bf16x8 a, bf16x8 b, f32x4 c) { return __builtin_amdgcn_mfma_f32_16x16x32_bf16(a, b, c, 0, 0, 0); }
; template <int MODE>
; PH void gemm_phase(const Params& p, int layer) {
;     ...
; #pragma unroll
;         for (int ks = 0; ks < 2; ++ks) {
;           bf16x8 wf[4], xf[4];
; #pragma unroll
;           for (int i = 0; i < 4; ++i) {
;             wf[i] = ldfrag(sW, 72, wn * 64 + i * 16, ks * 32, lane);
;             xf[i] = ldfrag(sX, 72, wm * 64 + i * 16, ks * 32, lane);
;           }
; #pragma unroll
;           for (int nt = 0; nt < 4; ++nt)
; #pragma unroll
;             for (int mt = 0; mt < 4; ++mt) acc[nt][mt] = mfma16(wf[nt], xf[mt], acc[nt][mt]);
;         }
	ds_read_b128 v[76:79], v70 offset:36864
	ds_read_b128 v[80:83], v71
	ds_read_b128 v[84:87], v70 offset:39168
	ds_read_b128 v[88:91], v71 offset:2304
	ds_read_b128 v[92:95], v70 offset:41472
	ds_read_b128 v[96:99], v71 offset:4608
	ds_read_b128 v[100:103], v70 offset:43776
	ds_read_b128 v[104:107], v71 offset:6912
	s_waitcnt lgkmcnt(6)
	v_mfma_f32_16x16x32_bf16 v[60:63], v[76:79], v[80:83], v[60:63]
	s_waitcnt lgkmcnt(4)
	v_mfma_f32_16x16x32_bf16 v[44:47], v[76:79], v[88:91], v[44:47]
	s_waitcnt lgkmcnt(2)
	v_mfma_f32_16x16x32_bf16 v[28:31], v[76:79], v[96:99], v[28:31]
	s_waitcnt lgkmcnt(0)
	v_mfma_f32_16x16x32_bf16 v[12:15], v[76:79], v[104:107], v[12:15]
	v_mfma_f32_16x16x32_bf16 v[56:59], v[84:87], v[80:83], v[56:59]
	v_mfma_f32_16x16x32_bf16 v[40:43], v[84:87], v[88:91], v[40:43]
	v_mfma_f32_16x16x32_bf16 v[24:27], v[84:87], v[96:99], v[24:27]
	v_mfma_f32_16x16x32_bf16 v[8:11], v[84:87], v[104:107], v[8:11]
	v_mfma_f32_16x16x32_bf16 v[52:55], v[92:95], v[80:83], v[52:55]
	v_mfma_f32_16x16x32_bf16 v[36:39], v[92:95], v[88:91], v[36:39]
	v_mfma_f32_16x16x32_bf16 v[20:23], v[92:95], v[96:99], v[20:23]
	v_mfma_f32_16x16x32_bf16 v[4:7], v[92:95], v[104:107], v[4:7]
	v_mfma_f32_16x16x32_bf16 v[48:51], v[100:103], v[80:83], v[48:51]
	v_mfma_f32_16x16x32_bf16 v[32:35], v[100:103], v[88:91], v[32:35]
	v_mfma_f32_16x16x32_bf16 v[16:19], v[100:103], v[96:99], v[16:19]
	v_mfma_f32_16x16x32_bf16 v[0:3], v[100:103], v[104:107], v[0:3]
	ds_read_b128 v[76:79], v70 offset:36928
	ds_read_b128 v[80:83], v71 offset:64
	ds_read_b128 v[84:87], v70 offset:39232
	ds_read_b128 v[88:91], v71 offset:2368
	ds_read_b128 v[92:95], v70 offset:41536
	ds_read_b128 v[96:99], v71 offset:4672
	ds_read_b128 v[100:103], v70 offset:43840
	ds_read_b128 v[104:107], v71 offset:6976
	s_waitcnt lgkmcnt(6)
	v_mfma_f32_16x16x32_bf16 v[60:63], v[76:79], v[80:83], v[60:63]
	s_waitcnt lgkmcnt(4)
	v_mfma_f32_16x16x32_bf16 v[44:47], v[76:79], v[88:91], v[44:47]
	s_waitcnt lgkmcnt(2)
	v_mfma_f32_16x16x32_bf16 v[28:31], v[76:79], v[96:99], v[28:31]
	s_waitcnt lgkmcnt(0)
	v_mfma_f32_16x16x32_bf16 v[12:15], v[76:79], v[104:107], v[12:15]
	v_mfma_f32_16x16x32_bf16 v[56:59], v[84:87], v[80:83], v[56:59]
	v_mfma_f32_16x16x32_bf16 v[40:43], v[84:87], v[88:91], v[40:43]
	v_mfma_f32_16x16x32_bf16 v[24:27], v[84:87], v[96:99], v[24:27]
	v_mfma_f32_16x16x32_bf16 v[8:11], v[84:87], v[104:107], v[8:11]
	v_mfma_f32_16x16x32_bf16 v[52:55], v[92:95], v[80:83], v[52:55]
	v_mfma_f32_16x16x32_bf16 v[36:39], v[92:95], v[88:91], v[36:39]
	v_mfma_f32_16x16x32_bf16 v[20:23], v[92:95], v[96:99], v[20:23]
	v_mfma_f32_16x16x32_bf16 v[4:7], v[92:95], v[104:107], v[4:7]
	v_mfma_f32_16x16x32_bf16 v[48:51], v[100:103], v[80:83], v[48:51]
	v_mfma_f32_16x16x32_bf16 v[32:35], v[100:103], v[88:91], v[32:35]
	v_mfma_f32_16x16x32_bf16 v[16:19], v[100:103], v[96:99], v[16:19]
	v_mfma_f32_16x16x32_bf16 v[0:3], v[100:103], v[104:107], v[0:3]
	s_waitcnt vmcnt(7)
	ds_write_b128 v75, v[108:111]
	s_waitcnt vmcnt(6)
	ds_write_b128 v75, v[112:115] offset:36864
	s_waitcnt vmcnt(5)
	ds_write_b128 v75, v[116:119] offset:4608
	s_waitcnt vmcnt(4)
	ds_write_b128 v75, v[120:123] offset:41472
	s_waitcnt vmcnt(3)
	ds_write_b128 v75, v[124:127] offset:9216
	s_waitcnt vmcnt(2)
	ds_write_b128 v75, v[128:131] offset:46080
	s_waitcnt vmcnt(1)
	ds_write_b128 v75, v[132:135] offset:13824
	s_waitcnt vmcnt(0)
	ds_write_b128 v75, v[136:139] offset:50688
	s_waitcnt lgkmcnt(0)
	s_barrier
; DI f32x4 mfma16(bf16x8 a, bf16x8 b, f32x4 c) { return __builtin_amdgcn_mfma_f32_16x16x32_bf16(a, b, c, 0, 0, 0); }
; template <int MODE>
; PH void gemm_phase(const Params& p, int layer) {
;     ...
; #pragma unroll
;         for (int ks = 0; ks < 2; ++ks) {
;           bf16x8 wf[4], xf[4];
; #pragma unroll
;           for (int i = 0; i < 4; ++i) {
;             wf[i] = ldfrag(sW, 72, wn * 64 + i * 16, ks * 32, lane);
;             xf[i] = ldfrag(sX, 72, wm * 64 + i * 16, ks * 32, lane);
;           }
; #pragma unroll
;           for (int nt = 0; nt < 4; ++nt)
; #pragma unroll
;             for (int mt = 0; mt < 4; ++mt) acc[nt][mt] = mfma16(wf[nt], xf[mt], acc[nt][mt]);
;         }
;       }
;       float* PRE = (float*)(p.ws + WS_PRE);
;       const float* SSQ = (const float*)(p.ws + WS_SSQ);
;       const float alpha = 1.681792830507429f;
; #pragma unroll
;       for (int mt = 0; mt < 4; ++mt) {
;         const int m = m0 + wm * 64 + mt * 16 + l15;
;         float rs = 1.f;
;         if (kq < 3) {
;           const float4 s0 = *(const float4*)(SSQ + (size_t)m * 12), s1 = *(const float4*)(SSQ + (size_t)m * 12 + 4), s2 = *(const float4*)(SSQ + (size_t)m * 12 + 8);
;           const float ss = s0.x + s0.y + s0.z + s0.w + s1.x + s1.y + s1.z + s1.w + s2.x + s2.y + s2.z + s2.w;
;           rs = rsqrtf(ss * (1.f / 768.f) + 1e-5f);
	ds_read_b128 v[76:79], v70 offset:55296
	ds_read_b128 v[80:83], v71 offset:18432
	ds_read_b128 v[84:87], v70 offset:57600
	ds_read_b128 v[88:91], v71 offset:20736
	ds_read_b128 v[92:95], v70 offset:59904
	ds_read_b128 v[96:99], v71 offset:23040
	ds_read_b128 v[100:103], v70 offset:62208
	ds_read_b128 v[104:107], v71 offset:25344
	s_waitcnt lgkmcnt(6)
	v_mfma_f32_16x16x32_bf16 v[60:63], v[76:79], v[80:83], v[60:63]
	s_waitcnt lgkmcnt(4)
	v_mfma_f32_16x16x32_bf16 v[44:47], v[76:79], v[88:91], v[44:47]
	s_waitcnt lgkmcnt(2)
	v_mfma_f32_16x16x32_bf16 v[28:31], v[76:79], v[96:99], v[28:31]
	s_waitcnt lgkmcnt(0)
	v_mfma_f32_16x16x32_bf16 v[12:15], v[76:79], v[104:107], v[12:15]
	v_mfma_f32_16x16x32_bf16 v[56:59], v[84:87], v[80:83], v[56:59]
	v_mfma_f32_16x16x32_bf16 v[40:43], v[84:87], v[88:91], v[40:43]
	v_mfma_f32_16x16x32_bf16 v[24:27], v[84:87], v[96:99], v[24:27]
	v_mfma_f32_16x16x32_bf16 v[8:11], v[84:87], v[104:107], v[8:11]
	v_mfma_f32_16x16x32_bf16 v[52:55], v[92:95], v[80:83], v[52:55]
	v_mfma_f32_16x16x32_bf16 v[36:39], v[92:95], v[88:91], v[36:39]
	v_mfma_f32_16x16x32_bf16 v[20:23], v[92:95], v[96:99], v[20:23]
	v_mfma_f32_16x16x32_bf16 v[4:7], v[92:95], v[104:107], v[4:7]
	v_mfma_f32_16x16x32_bf16 v[48:51], v[100:103], v[80:83], v[48:51]
	v_mfma_f32_16x16x32_bf16 v[32:35], v[100:103], v[88:91], v[32:35]
	v_mfma_f32_16x16x32_bf16 v[16:19], v[100:103], v[96:99], v[16:19]
	v_mfma_f32_16x16x32_bf16 v[0:3], v[100:103], v[104:107], v[0:3]
	ds_read_b128 v[76:79], v70 offset:55360
	ds_read_b128 v[80:83], v71 offset:18496
	ds_read_b128 v[84:87], v70 offset:57664
	ds_read_b128 v[88:91], v71 offset:20800
	ds_read_b128 v[92:95], v70 offset:59968
	ds_read_b128 v[96:99], v71 offset:23104
	ds_read_b128 v[100:103], v70 offset:62272
	ds_read_b128 v[104:107], v71 offset:25408
	s_waitcnt lgkmcnt(6)
	v_mfma_f32_16x16x32_bf16 v[60:63], v[76:79], v[80:83], v[60:63]
	s_waitcnt lgkmcnt(4)
	v_mfma_f32_16x16x32_bf16 v[44:47], v[76:79], v[88:91], v[44:47]
	s_waitcnt lgkmcnt(2)
	v_mfma_f32_16x16x32_bf16 v[28:31], v[76:79], v[96:99], v[28:31]
	s_waitcnt lgkmcnt(0)
	v_mfma_f32_16x16x32_bf16 v[12:15], v[76:79], v[104:107], v[12:15]
	v_mfma_f32_16x16x32_bf16 v[56:59], v[84:87], v[80:83], v[56:59]
	v_mfma_f32_16x16x32_bf16 v[40:43], v[84:87], v[88:91], v[40:43]
	v_mfma_f32_16x16x32_bf16 v[24:27], v[84:87], v[96:99], v[24:27]
	v_mfma_f32_16x16x32_bf16 v[8:11], v[84:87], v[104:107], v[8:11]
	v_mfma_f32_16x16x32_bf16 v[52:55], v[92:95], v[80:83], v[52:55]
	v_mfma_f32_16x16x32_bf16 v[36:39], v[92:95], v[88:91], v[36:39]
	v_mfma_f32_16x16x32_bf16 v[20:23], v[92:95], v[96:99], v[20:23]
	v_mfma_f32_16x16x32_bf16 v[4:7], v[92:95], v[104:107], v[4:7]
	v_mfma_f32_16x16x32_bf16 v[48:51], v[100:103], v[80:83], v[48:51]
	v_mfma_f32_16x16x32_bf16 v[32:35], v[100:103], v[88:91], v[32:35]
	v_mfma_f32_16x16x32_bf16 v[16:19], v[100:103], v[96:99], v[16:19]
	v_mfma_f32_16x16x32_bf16 v[0:3], v[100:103], v[104:107], v[0:3]
	s_movk_i32 s0, 0x100
	s_nop 0
	s_nop 0
	s_nop 0
	s_nop 0
	s_nop 0
	v_readlane_b32 s0, v254, 41
	v_readlane_b32 s1, v254, 42
	v_or_b32_e32 v64, 0x4000, v74
	v_mov_b32_e32 v75, 1.0
	s_and_b64 vcc, exec, s[0:1]
	s_cbranch_vccz .LBB0_775
	v_mul_u32_u24_e32 v65, 12, v64
	v_readlane_b32 s0, v254, 22
	v_lshlrev_b32_e32 v65, 2, v65
	v_readlane_b32 s1, v254, 23
	s_nop 4
	global_load_dwordx4 v[70:73], v65, s[0:1]
	global_load_dwordx4 v[76:79], v65, s[0:1] offset:16
	global_load_dwordx4 v[80:83], v65, s[0:1] offset:32
	s_mov_b32 s0, 0x800000
	s_waitcnt vmcnt(2)
	v_add_f32_e32 v65, v70, v71
	v_add_f32_e32 v65, v65, v72
	v_add_f32_e32 v65, v65, v73
	s_waitcnt vmcnt(1)
	v_add_f32_e32 v65, v65, v76
	v_add_f32_e32 v65, v65, v77
	v_add_f32_e32 v65, v65, v78
	v_add_f32_e32 v65, v65, v79
	s_waitcnt vmcnt(0)
	v_add_f32_e32 v65, v65, v80
	v_add_f32_e32 v65, v65, v81
	v_add_f32_e32 v65, v65, v82
	v_add_f32_e32 v65, v65, v83
	v_fmamk_f32 v65, v65, 0x3aaaaaab, v186
	v_mul_f32_e32 v66, 0x4b800000, v65
	v_cmp_gt_f32_e32 vcc, s0, v65
	s_nop 1
	v_cndmask_b32_e32 v65, v65, v66, vcc
	v_rsq_f32_e32 v65, v65
	s_nop 0
	v_mul_f32_e32 v66, 0x45800000, v65
	v_cndmask_b32_e32 v75, v65, v66, vcc

; DI unsigned xb_ld(unsigned* p)              { return __hip_atomic_load(p, __ATOMIC_RELAXED, __HIP_MEMORY_SCOPE_AGENT); }
; DI unsigned xb_add(unsigned* p, unsigned v) { return __hip_atomic_fetch_add(p, v, __ATOMIC_RELAXED, __HIP_MEMORY_SCOPE_AGENT); }
; #define XB_SPIN(cond, bar) do { unsigned _sp = 0; while (cond) { __builtin_amdgcn_s_sleep(1); \
;     if ((++_sp & 255u) == 0u) { if (xb_ld(&(bar)[XB_TMO])) break; if (_sp > XB_SPIN_CAP) { atomicAdd(&(bar)[XB_TMO], 1u); break; } } } } while (0)
; DI void xcd_barrier(const XcdBarrier& b) {
;     ...
;     const unsigned old = xb_add(&bar[XB_XSUB(b.x)], 1u);
;     const unsigned gen = old / nloc;
;     if (old + 1u == (gen + 1u) * nloc) {
;       __builtin_amdgcn_fence(__ATOMIC_RELEASE, "agent");
;       asm volatile("s_waitcnt vmcnt(0)" ::: "memory");
;       const unsigned og = xb_add(&bar[XB_TOP], 1u);
;       const unsigned tg = og / nx;
;       if (og + 1u == (tg + 1u) * nx) xb_add(&bar[XB_TOPGEN], 1u);
;       else XB_SPIN(xb_ld(&bar[XB_TOPGEN]) == tg, bar);
;       __builtin_amdgcn_fence(__ATOMIC_ACQUIRE, "agent");
;       xb_add(&bar[XB_XGEN(b.x)], 1u);
;       asm volatile("s_waitcnt vmcnt(0)" ::: "memory");
;     } else {
;       XB_SPIN(xb_ld(&bar[XB_XGEN(b.x)]) == gen, bar);
;       __builtin_amdgcn_fence(__ATOMIC_ACQUIRE, "agent");
;       asm volatile("s_waitcnt vmcnt(0)" ::: "memory");
;     }
.LBB0_983:
	s_bcnt1_i32_b64 s2, s[6:7]
	v_readlane_b32 s6, v253, 62
	v_mov_b32_e32 v0, s2
	v_readlane_b32 s7, v253, 63
	s_nop 4
	s_nop 0
	s_nop 0
	s_getpc_b64 s[98:99]
